# SGU: u-block loads and stores use a lane-transposed (row-contiguous per lane quad) mapping
# speedup vs baseline: 1.0304x; 1.0048x over previous
; __device__ __forceinline__ unsigned cvt_pk_bf16(float lo, float hi) { f32x2 v = {lo, hi}; bf16x2_t b = __builtin_convertvector(v, bf16x2_t); return __builtin_bit_cast(unsigned, b); }
; __device__ __forceinline__ float bf_lo(unsigned w) { return __uint_as_float(w << 16); }
; __device__ __forceinline__ float bf_hi(unsigned w) { return __uint_as_float(w & 0xffff0000u); }
; __device__ __forceinline__ f32x2 gelu_pk(f32x2 v) {
;     const f32x2 av = __builtin_elementwise_abs(v), d = av * 0.2316418882f + 1.0f;
;     f32x2 t; t.x = __builtin_amdgcn_rcpf(d.x); t.y = __builtin_amdgcn_rcpf(d.y);
;     f32x2 q = t * 0.5307027145f + (-0.7265760135f); q = q * t + 0.7107068705f; q = q * t + (-0.142248368f); q = q * t + 0.127414796f; q = q * t;
;     const f32x2 s = (v * v) * (-0.72134752044f);
;     f32x2 e; e.x = __builtin_amdgcn_exp2f(s.x); e.y = __builtin_amdgcn_exp2f(s.y);
;     const f32x2 m = v * (q * e), r = v - m;
;     f32x2 o; o.x = v.x < 0.f ? m.x : r.x; o.y = v.y < 0.f ? m.y : r.y; return o;
; }
; __device__ __forceinline__ void sgu_phase(KP kp, LAS unsigned char* lds, int l) {
;     ...
; #pragma unroll
;         for (int n = 0; n < 8; ++n) { u32x2 w;
;             const f32x2 ua = gelu_pk((f32x2){bf_lo(uu[n].x), bf_hi(uu[n].x)}), ub = gelu_pk((f32x2){bf_lo(uu[n].y), bf_hi(uu[n].y)});
;             w.x = cvt_pk_bf16(ua.x * (acc[n][0] + bias), ua.y * (acc[n][1] + bias)); w.y = cvt_pk_bf16(ub.x * (acc[n][2] + bias), ub.y * (acc[n][3] + bias));
;             *(u32x2*)(up + 16 * n) = w; }
.LBB0_77:
	s_or_b64 exec, exec, s[12:13]
	ds_bpermute_b32 v114, v211, v114
	ds_bpermute_b32 v115, v211, v115
	ds_bpermute_b32 v116, v211, v116
	ds_bpermute_b32 v117, v211, v117
	ds_bpermute_b32 v118, v211, v118
	ds_bpermute_b32 v119, v211, v119
	ds_bpermute_b32 v120, v211, v120
	ds_bpermute_b32 v121, v211, v121
	ds_bpermute_b32 v122, v211, v122
	ds_bpermute_b32 v123, v211, v123
	ds_bpermute_b32 v124, v211, v124
	ds_bpermute_b32 v125, v211, v125
	ds_bpermute_b32 v126, v211, v126
	ds_bpermute_b32 v127, v211, v127
	ds_bpermute_b32 v128, v211, v128
	ds_bpermute_b32 v129, v211, v129
	s_waitcnt lgkmcnt(0)
	v_lshlrev_b32_e32 v4, 16, v128
	v_and_b32_e32 v5, 0xffff0000, v128
	v_and_b32_e32 v3, 0x7fffffff, v5
	v_and_b32_e32 v2, 0x7fffffff, v4
	v_pk_fma_f32 v[2:3], v[2:3], s[14:15], 1.0 op_sel_hi:[1,0,0]
	s_mov_b32 s2, 0xbf3a00e3
	v_rcp_f32_e32 v6, v2
	v_rcp_f32_e32 v7, v3
	v_mov_b64_e32 v[2:3], s[2:3]
	v_pk_mul_f32 v[10:11], v[4:5], v[4:5]
	v_cmp_gt_f32_e32 vcc, 0, v5
	v_pk_fma_f32 v[8:9], v[6:7], s[38:39], v[2:3] op_sel_hi:[1,0,0]
	v_pk_mul_f32 v[10:11], v[10:11], s[18:19] op_sel_hi:[1,0]
	v_pk_fma_f32 v[8:9], v[6:7], v[8:9], s[10:11] op_sel_hi:[1,1,0]
	v_exp_f32_e32 v10, v10
	v_exp_f32_e32 v11, v11
	v_pk_fma_f32 v[8:9], v[6:7], v[8:9], s[56:57] op_sel_hi:[1,1,0]
	v_readlane_b32 s12, v252, 3
	v_pk_fma_f32 v[8:9], v[6:7], v[8:9], s[64:65] op_sel_hi:[1,1,0]
	s_add_i32 s20, s20, 1
	v_pk_mul_f32 v[6:7], v[6:7], v[8:9]
	s_add_i32 s21, s21, s12
	v_pk_mul_f32 v[6:7], v[10:11], v[6:7]
	v_pk_add_f32 v[10:11], v[110:111], v[46:47] op_sel_hi:[0,1]
	v_pk_mul_f32 v[8:9], v[6:7], v[4:5]
	v_pk_fma_f32 v[6:7], v[6:7], v[4:5], v[4:5] neg_lo:[1,0,0] neg_hi:[1,0,0]
	s_cmp_eq_u32 s15, s20
	v_cndmask_b32_e32 v5, v7, v9, vcc
	v_cmp_gt_f32_e32 vcc, 0, v4
	v_and_b32_e32 v7, 0xffff0000, v129
	v_and_b32_e32 v9, 0x7fffffff, v7
	v_cndmask_b32_e32 v4, v6, v8, vcc
	v_lshlrev_b32_e32 v6, 16, v129
	v_and_b32_e32 v8, 0x7fffffff, v6
	v_pk_fma_f32 v[8:9], v[8:9], s[14:15], 1.0 op_sel_hi:[1,0,0]
	v_pk_mul_f32 v[12:13], v[6:7], v[6:7]
	v_rcp_f32_e32 v8, v8
	v_rcp_f32_e32 v9, v9
	v_pk_mul_f32 v[4:5], v[4:5], v[10:11]
	v_pk_mul_f32 v[12:13], v[12:13], s[18:19] op_sel_hi:[1,0]
	v_cmp_gt_f32_e32 vcc, 0, v7
	v_pk_fma_f32 v[10:11], v[8:9], s[38:39], v[2:3] op_sel_hi:[1,0,0]
	v_exp_f32_e32 v12, v12
	v_pk_fma_f32 v[10:11], v[8:9], v[10:11], s[10:11] op_sel_hi:[1,1,0]
	v_exp_f32_e32 v13, v13
	v_pk_fma_f32 v[10:11], v[8:9], v[10:11], s[56:57] op_sel_hi:[1,1,0]
	v_cvt_pk_bf16_f32 v4, v4, v5
	v_pk_fma_f32 v[10:11], v[8:9], v[10:11], s[64:65] op_sel_hi:[1,1,0]
	v_readlane_b32 s13, v252, 4
	v_pk_mul_f32 v[8:9], v[8:9], v[10:11]
	s_nop 0
	v_pk_mul_f32 v[8:9], v[12:13], v[8:9]
	s_nop 0
	v_pk_mul_f32 v[10:11], v[8:9], v[6:7]
	v_pk_fma_f32 v[8:9], v[8:9], v[6:7], v[6:7] neg_lo:[1,0,0] neg_hi:[1,0,0]
	s_nop 0
	v_cndmask_b32_e32 v7, v9, v11, vcc
	v_cmp_gt_f32_e32 vcc, 0, v6
	v_and_b32_e32 v11, 0xffff0000, v126
	v_and_b32_e32 v13, 0x7fffffff, v11
	v_cndmask_b32_e32 v6, v8, v10, vcc
	v_lshlrev_b32_e32 v10, 16, v126
	v_and_b32_e32 v12, 0x7fffffff, v10
	v_pk_fma_f32 v[12:13], v[12:13], s[14:15], 1.0 op_sel_hi:[1,0,0]
	v_pk_add_f32 v[8:9], v[110:111], v[48:49] op_sel_hi:[0,1]
	v_rcp_f32_e32 v12, v12
	v_rcp_f32_e32 v13, v13
	v_pk_mul_f32 v[6:7], v[6:7], v[8:9]
	v_cmp_gt_f32_e32 vcc, 0, v11
	v_cvt_pk_bf16_f32 v5, v6, v7
	v_pk_mul_f32 v[6:7], v[10:11], v[10:11]
	ds_bpermute_b32 v216, v210, v4
	ds_bpermute_b32 v217, v210, v5
	v_pk_fma_f32 v[4:5], v[12:13], s[38:39], v[2:3] op_sel_hi:[1,0,0]
	v_pk_mul_f32 v[6:7], v[6:7], s[18:19] op_sel_hi:[1,0]
	v_pk_fma_f32 v[4:5], v[12:13], v[4:5], s[10:11] op_sel_hi:[1,1,0]
	v_exp_f32_e32 v6, v6
	v_exp_f32_e32 v7, v7
	v_pk_fma_f32 v[4:5], v[12:13], v[4:5], s[56:57] op_sel_hi:[1,1,0]
	s_nop 0
	v_pk_fma_f32 v[4:5], v[12:13], v[4:5], s[64:65] op_sel_hi:[1,1,0]
	s_nop 0
	v_pk_mul_f32 v[4:5], v[12:13], v[4:5]
	s_nop 0
	v_pk_mul_f32 v[4:5], v[6:7], v[4:5]
	s_nop 0
	v_pk_mul_f32 v[6:7], v[4:5], v[10:11]
	v_pk_fma_f32 v[4:5], v[4:5], v[10:11], v[10:11] neg_lo:[1,0,0] neg_hi:[1,0,0]
	s_nop 0
	v_cndmask_b32_e32 v5, v5, v7, vcc
	v_cmp_gt_f32_e32 vcc, 0, v10
	v_and_b32_e32 v7, 0xffff0000, v127
	v_and_b32_e32 v9, 0x7fffffff, v7
	v_cndmask_b32_e32 v4, v4, v6, vcc
	v_lshlrev_b32_e32 v6, 16, v127
	v_and_b32_e32 v8, 0x7fffffff, v6
	v_pk_fma_f32 v[8:9], v[8:9], s[14:15], 1.0 op_sel_hi:[1,0,0]
	v_pk_add_f32 v[10:11], v[110:111], v[42:43] op_sel_hi:[0,1]
	v_rcp_f32_e32 v8, v8
	v_rcp_f32_e32 v9, v9
	v_pk_mul_f32 v[12:13], v[6:7], v[6:7]
	v_pk_mul_f32 v[4:5], v[4:5], v[10:11]
	v_pk_mul_f32 v[12:13], v[12:13], s[18:19] op_sel_hi:[1,0]
	v_pk_fma_f32 v[10:11], v[8:9], s[38:39], v[2:3] op_sel_hi:[1,0,0]
	v_exp_f32_e32 v12, v12
	v_pk_fma_f32 v[10:11], v[8:9], v[10:11], s[10:11] op_sel_hi:[1,1,0]
	v_exp_f32_e32 v13, v13
	v_pk_fma_f32 v[10:11], v[8:9], v[10:11], s[56:57] op_sel_hi:[1,1,0]
	v_cmp_gt_f32_e32 vcc, 0, v7
	v_pk_fma_f32 v[10:11], v[8:9], v[10:11], s[64:65] op_sel_hi:[1,1,0]
	v_cvt_pk_bf16_f32 v4, v4, v5
	v_pk_mul_f32 v[8:9], v[8:9], v[10:11]
	s_nop 0
	v_pk_mul_f32 v[8:9], v[12:13], v[8:9]
	s_nop 0
	v_pk_mul_f32 v[10:11], v[8:9], v[6:7]
	v_pk_fma_f32 v[8:9], v[8:9], v[6:7], v[6:7] neg_lo:[1,0,0] neg_hi:[1,0,0]
	s_nop 0
	v_cndmask_b32_e32 v7, v9, v11, vcc
	v_cmp_gt_f32_e32 vcc, 0, v6
	v_and_b32_e32 v11, 0xffff0000, v124
	v_and_b32_e32 v13, 0x7fffffff, v11
	v_cndmask_b32_e32 v6, v8, v10, vcc
	v_lshlrev_b32_e32 v10, 16, v124
	v_and_b32_e32 v12, 0x7fffffff, v10
	v_pk_fma_f32 v[12:13], v[12:13], s[14:15], 1.0 op_sel_hi:[1,0,0]
	v_pk_add_f32 v[8:9], v[110:111], v[44:45] op_sel_hi:[0,1]
	v_rcp_f32_e32 v12, v12
	v_rcp_f32_e32 v13, v13
	v_pk_mul_f32 v[6:7], v[6:7], v[8:9]
	v_cmp_gt_f32_e32 vcc, 0, v11
	v_cvt_pk_bf16_f32 v5, v6, v7
	v_pk_mul_f32 v[6:7], v[10:11], v[10:11]
	s_waitcnt lgkmcnt(0)
; __device__ __forceinline__ unsigned cvt_pk_bf16(float lo, float hi) { f32x2 v = {lo, hi}; bf16x2_t b = __builtin_convertvector(v, bf16x2_t); return __builtin_bit_cast(unsigned, b); }
; __device__ __forceinline__ float bf_lo(unsigned w) { return __uint_as_float(w << 16); }
; __device__ __forceinline__ float bf_hi(unsigned w) { return __uint_as_float(w & 0xffff0000u); }
; __device__ __forceinline__ f32x2 gelu_pk(f32x2 v) {
;     const f32x2 av = __builtin_elementwise_abs(v), d = av * 0.2316418882f + 1.0f;
;     f32x2 t; t.x = __builtin_amdgcn_rcpf(d.x); t.y = __builtin_amdgcn_rcpf(d.y);
;     f32x2 q = t * 0.5307027145f + (-0.7265760135f); q = q * t + 0.7107068705f; q = q * t + (-0.142248368f); q = q * t + 0.127414796f; q = q * t;
;     const f32x2 s = (v * v) * (-0.72134752044f);
;     f32x2 e; e.x = __builtin_amdgcn_exp2f(s.x); e.y = __builtin_amdgcn_exp2f(s.y);
;     const f32x2 m = v * (q * e), r = v - m;
;     f32x2 o; o.x = v.x < 0.f ? m.x : r.x; o.y = v.y < 0.f ? m.y : r.y; return o;
; }
; __device__ __forceinline__ void sgu_phase(KP kp, LAS unsigned char* lds, int l) {
;     ...
; #pragma unroll
;         for (int n = 0; n < 8; ++n) { u32x2 w;
;             const f32x2 ua = gelu_pk((f32x2){bf_lo(uu[n].x), bf_hi(uu[n].x)}), ub = gelu_pk((f32x2){bf_lo(uu[n].y), bf_hi(uu[n].y)});
;             w.x = cvt_pk_bf16(ua.x * (acc[n][0] + bias), ua.y * (acc[n][1] + bias)); w.y = cvt_pk_bf16(ub.x * (acc[n][2] + bias), ub.y * (acc[n][3] + bias));
;             *(u32x2*)(up + 16 * n) = w; }
	global_store_dwordx2 v[112:113], v[216:217], off offset:2048
	ds_bpermute_b32 v218, v210, v4
	ds_bpermute_b32 v219, v210, v5
	v_pk_fma_f32 v[4:5], v[12:13], s[38:39], v[2:3] op_sel_hi:[1,0,0]
	v_pk_mul_f32 v[6:7], v[6:7], s[18:19] op_sel_hi:[1,0]
	v_pk_fma_f32 v[4:5], v[12:13], v[4:5], s[10:11] op_sel_hi:[1,1,0]
	v_exp_f32_e32 v6, v6
	v_exp_f32_e32 v7, v7
	v_pk_fma_f32 v[4:5], v[12:13], v[4:5], s[56:57] op_sel_hi:[1,1,0]
	s_nop 0
	v_pk_fma_f32 v[4:5], v[12:13], v[4:5], s[64:65] op_sel_hi:[1,1,0]
	s_nop 0
	v_pk_mul_f32 v[4:5], v[12:13], v[4:5]
	s_nop 0
	v_pk_mul_f32 v[4:5], v[6:7], v[4:5]
	s_nop 0
	v_pk_mul_f32 v[6:7], v[4:5], v[10:11]
	v_pk_fma_f32 v[4:5], v[4:5], v[10:11], v[10:11] neg_lo:[1,0,0] neg_hi:[1,0,0]
	s_nop 0
	v_cndmask_b32_e32 v5, v5, v7, vcc
	v_cmp_gt_f32_e32 vcc, 0, v10
	v_and_b32_e32 v7, 0xffff0000, v125
	v_and_b32_e32 v9, 0x7fffffff, v7
	v_cndmask_b32_e32 v4, v4, v6, vcc
	v_lshlrev_b32_e32 v6, 16, v125
	v_and_b32_e32 v8, 0x7fffffff, v6
	v_pk_fma_f32 v[8:9], v[8:9], s[14:15], 1.0 op_sel_hi:[1,0,0]
	v_pk_add_f32 v[10:11], v[110:111], v[38:39] op_sel_hi:[0,1]
	v_rcp_f32_e32 v8, v8
	v_rcp_f32_e32 v9, v9
	v_pk_mul_f32 v[12:13], v[6:7], v[6:7]
	v_pk_mul_f32 v[4:5], v[4:5], v[10:11]
	v_pk_mul_f32 v[12:13], v[12:13], s[18:19] op_sel_hi:[1,0]
	v_pk_fma_f32 v[10:11], v[8:9], s[38:39], v[2:3] op_sel_hi:[1,0,0]
	v_exp_f32_e32 v12, v12
	v_pk_fma_f32 v[10:11], v[8:9], v[10:11], s[10:11] op_sel_hi:[1,1,0]
	v_exp_f32_e32 v13, v13
	v_pk_fma_f32 v[10:11], v[8:9], v[10:11], s[56:57] op_sel_hi:[1,1,0]
	v_cmp_gt_f32_e32 vcc, 0, v7
	v_pk_fma_f32 v[10:11], v[8:9], v[10:11], s[64:65] op_sel_hi:[1,1,0]
	v_cvt_pk_bf16_f32 v4, v4, v5
	v_pk_mul_f32 v[8:9], v[8:9], v[10:11]
	s_nop 0
	v_pk_mul_f32 v[8:9], v[12:13], v[8:9]
	s_nop 0
	v_pk_mul_f32 v[10:11], v[8:9], v[6:7]
	v_pk_fma_f32 v[8:9], v[8:9], v[6:7], v[6:7] neg_lo:[1,0,0] neg_hi:[1,0,0]
	s_nop 0
	v_cndmask_b32_e32 v7, v9, v11, vcc
	v_cmp_gt_f32_e32 vcc, 0, v6
	v_and_b32_e32 v11, 0xffff0000, v122
	v_and_b32_e32 v13, 0x7fffffff, v11
	v_cndmask_b32_e32 v6, v8, v10, vcc
	v_lshlrev_b32_e32 v10, 16, v122
	v_and_b32_e32 v12, 0x7fffffff, v10
	v_pk_fma_f32 v[12:13], v[12:13], s[14:15], 1.0 op_sel_hi:[1,0,0]
	v_pk_add_f32 v[8:9], v[110:111], v[40:41] op_sel_hi:[0,1]
	v_rcp_f32_e32 v12, v12
	v_rcp_f32_e32 v13, v13
	v_pk_mul_f32 v[6:7], v[6:7], v[8:9]
	v_cmp_gt_f32_e32 vcc, 0, v11
	v_cvt_pk_bf16_f32 v5, v6, v7
	v_pk_mul_f32 v[6:7], v[10:11], v[10:11]
	s_waitcnt lgkmcnt(0)
	global_store_dwordx2 v[112:113], v[218:219], off offset:2080
	ds_bpermute_b32 v216, v210, v4
	ds_bpermute_b32 v217, v210, v5
	v_pk_fma_f32 v[4:5], v[12:13], s[38:39], v[2:3] op_sel_hi:[1,0,0]
	v_pk_mul_f32 v[6:7], v[6:7], s[18:19] op_sel_hi:[1,0]
	v_pk_fma_f32 v[4:5], v[12:13], v[4:5], s[10:11] op_sel_hi:[1,1,0]
	v_exp_f32_e32 v6, v6
	v_exp_f32_e32 v7, v7
	v_pk_fma_f32 v[4:5], v[12:13], v[4:5], s[56:57] op_sel_hi:[1,1,0]
	s_nop 0
	v_pk_fma_f32 v[4:5], v[12:13], v[4:5], s[64:65] op_sel_hi:[1,1,0]
	s_nop 0
	v_pk_mul_f32 v[4:5], v[12:13], v[4:5]
	s_nop 0
	v_pk_mul_f32 v[4:5], v[6:7], v[4:5]
	s_nop 0
	v_pk_mul_f32 v[6:7], v[4:5], v[10:11]
	v_pk_fma_f32 v[4:5], v[4:5], v[10:11], v[10:11] neg_lo:[1,0,0] neg_hi:[1,0,0]
	s_nop 0
	v_cndmask_b32_e32 v5, v5, v7, vcc
	v_cmp_gt_f32_e32 vcc, 0, v10
	v_and_b32_e32 v7, 0xffff0000, v123
	v_and_b32_e32 v9, 0x7fffffff, v7
	v_cndmask_b32_e32 v4, v4, v6, vcc
	v_lshlrev_b32_e32 v6, 16, v123
	v_and_b32_e32 v8, 0x7fffffff, v6
	v_pk_fma_f32 v[8:9], v[8:9], s[14:15], 1.0 op_sel_hi:[1,0,0]
	v_pk_add_f32 v[10:11], v[110:111], v[34:35] op_sel_hi:[0,1]
	v_rcp_f32_e32 v8, v8
	v_rcp_f32_e32 v9, v9
	v_pk_mul_f32 v[12:13], v[6:7], v[6:7]
	v_pk_mul_f32 v[4:5], v[4:5], v[10:11]
	v_pk_mul_f32 v[12:13], v[12:13], s[18:19] op_sel_hi:[1,0]
	v_pk_fma_f32 v[10:11], v[8:9], s[38:39], v[2:3] op_sel_hi:[1,0,0]
	v_exp_f32_e32 v12, v12
	v_pk_fma_f32 v[10:11], v[8:9], v[10:11], s[10:11] op_sel_hi:[1,1,0]
	v_exp_f32_e32 v13, v13
	v_pk_fma_f32 v[10:11], v[8:9], v[10:11], s[56:57] op_sel_hi:[1,1,0]
	v_cmp_gt_f32_e32 vcc, 0, v7
	v_pk_fma_f32 v[10:11], v[8:9], v[10:11], s[64:65] op_sel_hi:[1,1,0]
	v_cvt_pk_bf16_f32 v4, v4, v5
	v_pk_mul_f32 v[8:9], v[8:9], v[10:11]
	s_nop 0
	v_pk_mul_f32 v[8:9], v[12:13], v[8:9]
	s_nop 0
	v_pk_mul_f32 v[10:11], v[8:9], v[6:7]
	v_pk_fma_f32 v[8:9], v[8:9], v[6:7], v[6:7] neg_lo:[1,0,0] neg_hi:[1,0,0]
	s_nop 0
	v_cndmask_b32_e32 v7, v9, v11, vcc
	v_cmp_gt_f32_e32 vcc, 0, v6
	v_and_b32_e32 v11, 0xffff0000, v120
	v_and_b32_e32 v13, 0x7fffffff, v11
	v_cndmask_b32_e32 v6, v8, v10, vcc
	v_lshlrev_b32_e32 v10, 16, v120
	v_and_b32_e32 v12, 0x7fffffff, v10
	v_pk_fma_f32 v[12:13], v[12:13], s[14:15], 1.0 op_sel_hi:[1,0,0]
	v_pk_add_f32 v[8:9], v[110:111], v[36:37] op_sel_hi:[0,1]
	v_rcp_f32_e32 v12, v12
	v_rcp_f32_e32 v13, v13
	v_pk_mul_f32 v[6:7], v[6:7], v[8:9]
	v_cmp_gt_f32_e32 vcc, 0, v11
	v_cvt_pk_bf16_f32 v5, v6, v7
	v_pk_mul_f32 v[6:7], v[10:11], v[10:11]
	s_waitcnt lgkmcnt(0)
; __device__ __forceinline__ unsigned cvt_pk_bf16(float lo, float hi) { f32x2 v = {lo, hi}; bf16x2_t b = __builtin_convertvector(v, bf16x2_t); return __builtin_bit_cast(unsigned, b); }
; __device__ __forceinline__ float bf_lo(unsigned w) { return __uint_as_float(w << 16); }
; __device__ __forceinline__ float bf_hi(unsigned w) { return __uint_as_float(w & 0xffff0000u); }
; __device__ __forceinline__ f32x2 gelu_pk(f32x2 v) {
;     const f32x2 av = __builtin_elementwise_abs(v), d = av * 0.2316418882f + 1.0f;
;     f32x2 t; t.x = __builtin_amdgcn_rcpf(d.x); t.y = __builtin_amdgcn_rcpf(d.y);
;     f32x2 q = t * 0.5307027145f + (-0.7265760135f); q = q * t + 0.7107068705f; q = q * t + (-0.142248368f); q = q * t + 0.127414796f; q = q * t;
;     const f32x2 s = (v * v) * (-0.72134752044f);
;     f32x2 e; e.x = __builtin_amdgcn_exp2f(s.x); e.y = __builtin_amdgcn_exp2f(s.y);
;     const f32x2 m = v * (q * e), r = v - m;
;     f32x2 o; o.x = v.x < 0.f ? m.x : r.x; o.y = v.y < 0.f ? m.y : r.y; return o;
; }
; __device__ __forceinline__ void sgu_phase(KP kp, LAS unsigned char* lds, int l) {
;     ...
; #pragma unroll
;         for (int n = 0; n < 8; ++n) { u32x2 w;
;             const f32x2 ua = gelu_pk((f32x2){bf_lo(uu[n].x), bf_hi(uu[n].x)}), ub = gelu_pk((f32x2){bf_lo(uu[n].y), bf_hi(uu[n].y)});
;             w.x = cvt_pk_bf16(ua.x * (acc[n][0] + bias), ua.y * (acc[n][1] + bias)); w.y = cvt_pk_bf16(ub.x * (acc[n][2] + bias), ub.y * (acc[n][3] + bias));
;             *(u32x2*)(up + 16 * n) = w; }
	global_store_dwordx2 v[112:113], v[216:217], off offset:2112
	ds_bpermute_b32 v218, v210, v4
	ds_bpermute_b32 v219, v210, v5
	v_pk_fma_f32 v[4:5], v[12:13], s[38:39], v[2:3] op_sel_hi:[1,0,0]
	v_pk_mul_f32 v[6:7], v[6:7], s[18:19] op_sel_hi:[1,0]
	v_pk_fma_f32 v[4:5], v[12:13], v[4:5], s[10:11] op_sel_hi:[1,1,0]
	v_exp_f32_e32 v6, v6
	v_exp_f32_e32 v7, v7
	v_pk_fma_f32 v[4:5], v[12:13], v[4:5], s[56:57] op_sel_hi:[1,1,0]
	s_nop 0
	v_pk_fma_f32 v[4:5], v[12:13], v[4:5], s[64:65] op_sel_hi:[1,1,0]
	s_nop 0
	v_pk_mul_f32 v[4:5], v[12:13], v[4:5]
	s_nop 0
	v_pk_mul_f32 v[4:5], v[6:7], v[4:5]
	s_nop 0
	v_pk_mul_f32 v[6:7], v[4:5], v[10:11]
	v_pk_fma_f32 v[4:5], v[4:5], v[10:11], v[10:11] neg_lo:[1,0,0] neg_hi:[1,0,0]
	s_nop 0
	v_cndmask_b32_e32 v5, v5, v7, vcc
	v_cmp_gt_f32_e32 vcc, 0, v10
	v_and_b32_e32 v7, 0xffff0000, v121
	v_and_b32_e32 v9, 0x7fffffff, v7
	v_cndmask_b32_e32 v4, v4, v6, vcc
	v_lshlrev_b32_e32 v6, 16, v121
	v_and_b32_e32 v8, 0x7fffffff, v6
	v_pk_fma_f32 v[8:9], v[8:9], s[14:15], 1.0 op_sel_hi:[1,0,0]
	v_pk_add_f32 v[10:11], v[110:111], v[30:31] op_sel_hi:[0,1]
	v_rcp_f32_e32 v8, v8
	v_rcp_f32_e32 v9, v9
	v_pk_mul_f32 v[12:13], v[6:7], v[6:7]
	v_pk_mul_f32 v[4:5], v[4:5], v[10:11]
	v_pk_mul_f32 v[12:13], v[12:13], s[18:19] op_sel_hi:[1,0]
	v_pk_fma_f32 v[10:11], v[8:9], s[38:39], v[2:3] op_sel_hi:[1,0,0]
	v_exp_f32_e32 v12, v12
	v_pk_fma_f32 v[10:11], v[8:9], v[10:11], s[10:11] op_sel_hi:[1,1,0]
	v_exp_f32_e32 v13, v13
	v_pk_fma_f32 v[10:11], v[8:9], v[10:11], s[56:57] op_sel_hi:[1,1,0]
	v_cmp_gt_f32_e32 vcc, 0, v7
	v_pk_fma_f32 v[10:11], v[8:9], v[10:11], s[64:65] op_sel_hi:[1,1,0]
	v_cvt_pk_bf16_f32 v4, v4, v5
	v_pk_mul_f32 v[8:9], v[8:9], v[10:11]
	s_nop 0
	v_pk_mul_f32 v[8:9], v[12:13], v[8:9]
	s_nop 0
	v_pk_mul_f32 v[10:11], v[8:9], v[6:7]
	v_pk_fma_f32 v[8:9], v[8:9], v[6:7], v[6:7] neg_lo:[1,0,0] neg_hi:[1,0,0]
	s_nop 0
	v_cndmask_b32_e32 v7, v9, v11, vcc
	v_cmp_gt_f32_e32 vcc, 0, v6
	v_and_b32_e32 v11, 0xffff0000, v118
	v_and_b32_e32 v13, 0x7fffffff, v11
	v_cndmask_b32_e32 v6, v8, v10, vcc
	v_lshlrev_b32_e32 v10, 16, v118
	v_and_b32_e32 v12, 0x7fffffff, v10
	v_pk_fma_f32 v[12:13], v[12:13], s[14:15], 1.0 op_sel_hi:[1,0,0]
	v_pk_add_f32 v[8:9], v[110:111], v[32:33] op_sel_hi:[0,1]
	v_rcp_f32_e32 v12, v12
	v_rcp_f32_e32 v13, v13
	v_pk_mul_f32 v[6:7], v[6:7], v[8:9]
	v_cmp_gt_f32_e32 vcc, 0, v11
	v_cvt_pk_bf16_f32 v5, v6, v7
	v_pk_mul_f32 v[6:7], v[10:11], v[10:11]
	s_waitcnt lgkmcnt(0)
	global_store_dwordx2 v[112:113], v[218:219], off offset:2144
	ds_bpermute_b32 v216, v210, v4
	ds_bpermute_b32 v217, v210, v5
	v_pk_fma_f32 v[4:5], v[12:13], s[38:39], v[2:3] op_sel_hi:[1,0,0]
	v_pk_mul_f32 v[6:7], v[6:7], s[18:19] op_sel_hi:[1,0]
	v_pk_fma_f32 v[4:5], v[12:13], v[4:5], s[10:11] op_sel_hi:[1,1,0]
	v_exp_f32_e32 v6, v6
	v_exp_f32_e32 v7, v7
	v_pk_fma_f32 v[4:5], v[12:13], v[4:5], s[56:57] op_sel_hi:[1,1,0]
	s_nop 0
	v_pk_fma_f32 v[4:5], v[12:13], v[4:5], s[64:65] op_sel_hi:[1,1,0]
	s_nop 0
	v_pk_mul_f32 v[4:5], v[12:13], v[4:5]
	s_nop 0
	v_pk_mul_f32 v[4:5], v[6:7], v[4:5]
	s_nop 0
	v_pk_mul_f32 v[6:7], v[4:5], v[10:11]
	v_pk_fma_f32 v[4:5], v[4:5], v[10:11], v[10:11] neg_lo:[1,0,0] neg_hi:[1,0,0]
	s_nop 0
	v_cndmask_b32_e32 v5, v5, v7, vcc
	v_cmp_gt_f32_e32 vcc, 0, v10
	v_and_b32_e32 v7, 0xffff0000, v119
	v_and_b32_e32 v9, 0x7fffffff, v7
	v_cndmask_b32_e32 v4, v4, v6, vcc
	v_lshlrev_b32_e32 v6, 16, v119
	v_and_b32_e32 v8, 0x7fffffff, v6
	v_pk_fma_f32 v[8:9], v[8:9], s[14:15], 1.0 op_sel_hi:[1,0,0]
	v_pk_add_f32 v[10:11], v[110:111], v[26:27] op_sel_hi:[0,1]
	v_rcp_f32_e32 v8, v8
	v_rcp_f32_e32 v9, v9
	v_pk_mul_f32 v[12:13], v[6:7], v[6:7]
	v_pk_mul_f32 v[4:5], v[4:5], v[10:11]
	v_pk_mul_f32 v[12:13], v[12:13], s[18:19] op_sel_hi:[1,0]
	v_pk_fma_f32 v[10:11], v[8:9], s[38:39], v[2:3] op_sel_hi:[1,0,0]
	v_exp_f32_e32 v12, v12
	v_pk_fma_f32 v[10:11], v[8:9], v[10:11], s[10:11] op_sel_hi:[1,1,0]
	v_exp_f32_e32 v13, v13
	v_pk_fma_f32 v[10:11], v[8:9], v[10:11], s[56:57] op_sel_hi:[1,1,0]
	v_cmp_gt_f32_e32 vcc, 0, v7
	v_pk_fma_f32 v[10:11], v[8:9], v[10:11], s[64:65] op_sel_hi:[1,1,0]
	v_cvt_pk_bf16_f32 v4, v4, v5
	v_pk_mul_f32 v[8:9], v[8:9], v[10:11]
	s_nop 0
	v_pk_mul_f32 v[8:9], v[12:13], v[8:9]
	s_nop 0
	v_pk_mul_f32 v[10:11], v[8:9], v[6:7]
	v_pk_fma_f32 v[8:9], v[8:9], v[6:7], v[6:7] neg_lo:[1,0,0] neg_hi:[1,0,0]
	s_nop 0
	v_cndmask_b32_e32 v7, v9, v11, vcc
	v_cmp_gt_f32_e32 vcc, 0, v6
	v_and_b32_e32 v11, 0xffff0000, v116
	v_and_b32_e32 v13, 0x7fffffff, v11
	v_cndmask_b32_e32 v6, v8, v10, vcc
	v_lshlrev_b32_e32 v10, 16, v116
	v_and_b32_e32 v12, 0x7fffffff, v10
	v_pk_fma_f32 v[12:13], v[12:13], s[14:15], 1.0 op_sel_hi:[1,0,0]
	v_pk_add_f32 v[8:9], v[110:111], v[28:29] op_sel_hi:[0,1]
	v_rcp_f32_e32 v12, v12
	v_rcp_f32_e32 v13, v13
	v_pk_mul_f32 v[6:7], v[6:7], v[8:9]
	v_cmp_gt_f32_e32 vcc, 0, v11
	v_cvt_pk_bf16_f32 v5, v6, v7
	v_pk_mul_f32 v[6:7], v[10:11], v[10:11]
	s_waitcnt lgkmcnt(0)
; __device__ __forceinline__ unsigned cvt_pk_bf16(float lo, float hi) { f32x2 v = {lo, hi}; bf16x2_t b = __builtin_convertvector(v, bf16x2_t); return __builtin_bit_cast(unsigned, b); }
; __device__ __forceinline__ float bf_lo(unsigned w) { return __uint_as_float(w << 16); }
; __device__ __forceinline__ float bf_hi(unsigned w) { return __uint_as_float(w & 0xffff0000u); }
; __device__ __forceinline__ f32x2 gelu_pk(f32x2 v) {
;     const f32x2 av = __builtin_elementwise_abs(v), d = av * 0.2316418882f + 1.0f;
;     f32x2 t; t.x = __builtin_amdgcn_rcpf(d.x); t.y = __builtin_amdgcn_rcpf(d.y);
;     f32x2 q = t * 0.5307027145f + (-0.7265760135f); q = q * t + 0.7107068705f; q = q * t + (-0.142248368f); q = q * t + 0.127414796f; q = q * t;
;     const f32x2 s = (v * v) * (-0.72134752044f);
;     f32x2 e; e.x = __builtin_amdgcn_exp2f(s.x); e.y = __builtin_amdgcn_exp2f(s.y);
;     const f32x2 m = v * (q * e), r = v - m;
;     f32x2 o; o.x = v.x < 0.f ? m.x : r.x; o.y = v.y < 0.f ? m.y : r.y; return o;
; }
; __device__ __forceinline__ void sgu_phase(KP kp, LAS unsigned char* lds, int l) {
;     ...
; #pragma unroll
;         for (int n = 0; n < 8; ++n) { u32x2 w;
;             const f32x2 ua = gelu_pk((f32x2){bf_lo(uu[n].x), bf_hi(uu[n].x)}), ub = gelu_pk((f32x2){bf_lo(uu[n].y), bf_hi(uu[n].y)});
;             w.x = cvt_pk_bf16(ua.x * (acc[n][0] + bias), ua.y * (acc[n][1] + bias)); w.y = cvt_pk_bf16(ub.x * (acc[n][2] + bias), ub.y * (acc[n][3] + bias));
;             *(u32x2*)(up + 16 * n) = w; }
	global_store_dwordx2 v[112:113], v[216:217], off offset:2176
	ds_bpermute_b32 v218, v210, v4
	ds_bpermute_b32 v219, v210, v5
	v_pk_fma_f32 v[4:5], v[12:13], s[38:39], v[2:3] op_sel_hi:[1,0,0]
	v_pk_mul_f32 v[6:7], v[6:7], s[18:19] op_sel_hi:[1,0]
	v_pk_fma_f32 v[4:5], v[12:13], v[4:5], s[10:11] op_sel_hi:[1,1,0]
	v_exp_f32_e32 v6, v6
	v_exp_f32_e32 v7, v7
	v_pk_fma_f32 v[4:5], v[12:13], v[4:5], s[56:57] op_sel_hi:[1,1,0]
	s_nop 0
	v_pk_fma_f32 v[4:5], v[12:13], v[4:5], s[64:65] op_sel_hi:[1,1,0]
	s_nop 0
	v_pk_mul_f32 v[4:5], v[12:13], v[4:5]
	s_nop 0
	v_pk_mul_f32 v[4:5], v[6:7], v[4:5]
	s_nop 0
	v_pk_mul_f32 v[6:7], v[4:5], v[10:11]
	v_pk_fma_f32 v[4:5], v[4:5], v[10:11], v[10:11] neg_lo:[1,0,0] neg_hi:[1,0,0]
	s_nop 0
	v_cndmask_b32_e32 v5, v5, v7, vcc
	v_cmp_gt_f32_e32 vcc, 0, v10
	v_and_b32_e32 v7, 0xffff0000, v117
	v_and_b32_e32 v9, 0x7fffffff, v7
	v_cndmask_b32_e32 v4, v4, v6, vcc
	v_lshlrev_b32_e32 v6, 16, v117
	v_and_b32_e32 v8, 0x7fffffff, v6
	v_pk_fma_f32 v[8:9], v[8:9], s[14:15], 1.0 op_sel_hi:[1,0,0]
	v_pk_add_f32 v[10:11], v[110:111], v[22:23] op_sel_hi:[0,1]
	v_rcp_f32_e32 v8, v8
	v_rcp_f32_e32 v9, v9
	v_pk_mul_f32 v[12:13], v[6:7], v[6:7]
	v_pk_mul_f32 v[4:5], v[4:5], v[10:11]
	v_pk_mul_f32 v[12:13], v[12:13], s[18:19] op_sel_hi:[1,0]
	v_pk_fma_f32 v[10:11], v[8:9], s[38:39], v[2:3] op_sel_hi:[1,0,0]
	v_exp_f32_e32 v12, v12
	v_pk_fma_f32 v[10:11], v[8:9], v[10:11], s[10:11] op_sel_hi:[1,1,0]
	v_exp_f32_e32 v13, v13
	v_pk_fma_f32 v[10:11], v[8:9], v[10:11], s[56:57] op_sel_hi:[1,1,0]
	v_cmp_gt_f32_e32 vcc, 0, v7
	v_pk_fma_f32 v[10:11], v[8:9], v[10:11], s[64:65] op_sel_hi:[1,1,0]
	v_cvt_pk_bf16_f32 v4, v4, v5
	v_pk_mul_f32 v[8:9], v[8:9], v[10:11]
	s_nop 0
	v_pk_mul_f32 v[8:9], v[12:13], v[8:9]
	s_nop 0
	v_pk_mul_f32 v[10:11], v[8:9], v[6:7]
	v_pk_fma_f32 v[8:9], v[8:9], v[6:7], v[6:7] neg_lo:[1,0,0] neg_hi:[1,0,0]
	s_nop 0
	v_cndmask_b32_e32 v7, v9, v11, vcc
	v_cmp_gt_f32_e32 vcc, 0, v6
	v_and_b32_e32 v11, 0xffff0000, v114
	v_and_b32_e32 v13, 0x7fffffff, v11
	v_cndmask_b32_e32 v6, v8, v10, vcc
	v_lshlrev_b32_e32 v10, 16, v114
	v_and_b32_e32 v12, 0x7fffffff, v10
	v_pk_fma_f32 v[12:13], v[12:13], s[14:15], 1.0 op_sel_hi:[1,0,0]
	v_pk_add_f32 v[8:9], v[110:111], v[24:25] op_sel_hi:[0,1]
	v_rcp_f32_e32 v12, v12
	v_rcp_f32_e32 v13, v13
	v_pk_mul_f32 v[6:7], v[6:7], v[8:9]
	v_cmp_gt_f32_e32 vcc, 0, v11
	v_cvt_pk_bf16_f32 v5, v6, v7
	v_pk_mul_f32 v[6:7], v[10:11], v[10:11]
	s_waitcnt lgkmcnt(0)
	global_store_dwordx2 v[112:113], v[218:219], off offset:2208
	ds_bpermute_b32 v216, v210, v4
	ds_bpermute_b32 v217, v210, v5
	v_pk_fma_f32 v[4:5], v[12:13], s[38:39], v[2:3] op_sel_hi:[1,0,0]
	v_pk_mul_f32 v[6:7], v[6:7], s[18:19] op_sel_hi:[1,0]
	v_pk_fma_f32 v[4:5], v[12:13], v[4:5], s[10:11] op_sel_hi:[1,1,0]
	v_exp_f32_e32 v6, v6
	v_exp_f32_e32 v7, v7
	v_pk_fma_f32 v[4:5], v[12:13], v[4:5], s[56:57] op_sel_hi:[1,1,0]
	s_nop 0
	v_pk_fma_f32 v[4:5], v[12:13], v[4:5], s[64:65] op_sel_hi:[1,1,0]
	s_nop 0
	v_pk_mul_f32 v[4:5], v[12:13], v[4:5]
	s_nop 0
	v_pk_mul_f32 v[4:5], v[6:7], v[4:5]
	s_nop 0
	v_pk_mul_f32 v[6:7], v[4:5], v[10:11]
	v_pk_fma_f32 v[4:5], v[4:5], v[10:11], v[10:11] neg_lo:[1,0,0] neg_hi:[1,0,0]
	s_nop 0
	v_cndmask_b32_e32 v5, v5, v7, vcc
	v_cmp_gt_f32_e32 vcc, 0, v10
	v_and_b32_e32 v7, 0xffff0000, v115
	v_and_b32_e32 v9, 0x7fffffff, v7
	v_cndmask_b32_e32 v4, v4, v6, vcc
	v_lshlrev_b32_e32 v6, 16, v115
	v_and_b32_e32 v8, 0x7fffffff, v6
	v_pk_fma_f32 v[8:9], v[8:9], s[14:15], 1.0 op_sel_hi:[1,0,0]
	v_pk_add_f32 v[10:11], v[110:111], v[18:19] op_sel_hi:[0,1]
	v_rcp_f32_e32 v8, v8
	v_rcp_f32_e32 v9, v9
	v_pk_mul_f32 v[4:5], v[4:5], v[10:11]
	v_pk_mul_f32 v[10:11], v[6:7], v[6:7]
	v_cmp_gt_f32_e32 vcc, 0, v7
	v_pk_fma_f32 v[2:3], v[8:9], s[38:39], v[2:3] op_sel_hi:[1,0,0]
	v_pk_mul_f32 v[10:11], v[10:11], s[18:19] op_sel_hi:[1,0]
	v_pk_fma_f32 v[2:3], v[8:9], v[2:3], s[10:11] op_sel_hi:[1,1,0]
	v_exp_f32_e32 v10, v10
	v_exp_f32_e32 v11, v11
	v_pk_fma_f32 v[2:3], v[8:9], v[2:3], s[56:57] op_sel_hi:[1,1,0]
	v_cvt_pk_bf16_f32 v4, v4, v5
	v_pk_fma_f32 v[2:3], v[8:9], v[2:3], s[64:65] op_sel_hi:[1,1,0]
	s_nop 0
	v_pk_mul_f32 v[2:3], v[8:9], v[2:3]
	s_nop 0
	v_pk_mul_f32 v[2:3], v[10:11], v[2:3]
	s_nop 0
	v_pk_mul_f32 v[8:9], v[2:3], v[6:7]
	v_pk_fma_f32 v[2:3], v[2:3], v[6:7], v[6:7] neg_lo:[1,0,0] neg_hi:[1,0,0]
	s_nop 0
	v_cndmask_b32_e32 v3, v3, v9, vcc
	v_cmp_gt_f32_e32 vcc, 0, v6
	v_pk_add_f32 v[6:7], v[110:111], v[20:21] op_sel_hi:[0,1]
	s_nop 0
	v_cndmask_b32_e32 v2, v2, v8, vcc
	v_pk_mul_f32 v[2:3], v[2:3], v[6:7]
	s_nop 0
	v_cvt_pk_bf16_f32 v5, v2, v3
	s_waitcnt lgkmcnt(0)
	global_store_dwordx2 v[112:113], v[216:217], off offset:2240
	ds_bpermute_b32 v218, v210, v4
	ds_bpermute_b32 v219, v210, v5
	s_waitcnt lgkmcnt(0)
	global_store_dwordx2 v[112:113], v[218:219], off offset:2272
	s_barrier
	s_cbranch_scc1 .LBB0_135

; __device__ __forceinline__ void sgu_phase(KP kp, LAS unsigned char* lds, int l) {
;     ...
;         const int t = 16 * wid + fr; const float bias = bsp[h * 128 + t]; bf16_t* up = Z + (size_t)(r0 + t) * NIN + 1024 + h * 128 + 4 * fq;
;         u32x2 uu[8];
; #pragma unroll
;         for (int n = 0; n < 8; ++n) uu[n] = *(const u32x2*)(up + 16 * n);
;         { const int w = 2 << (h >> 1), pc = tid & 15, pr = (tid >> 4) * 4, t0 = (r0 + pr) & (SEQ - 1);
;           const bf16_t* src = Z + (size_t)(r0 + pr) * NIN + h * 128 + pc * 8;
;           float ps[8];
; #pragma unroll
;           for (int e = 0; e < 8; ++e) ps[e] = 0.f;
;           { u32x4 hw[15];
; #pragma unroll
;             for (int j = 1; j < 16; ++j) hw[j - 1] = (j < w && t0 - j >= 0) ? *(const u32x4*)(src - (size_t)j * NIN) : (u32x4){0u, 0u, 0u, 0u};
.LBB0_90:
	s_or_b64 exec, exec, s[16:17]
	v_lshl_add_u64 v[18:19], v[18:19], 2, s[8:9]
	global_load_dword v110, v[18:19], off
	v_add_u32_e32 v20, s12, v135
	v_mov_b64_e32 v[18:19], s[70:71]
	v_mad_i64_i32 v[20:21], s[16:17], v20, s69, v[18:19]
	s_lshl_b32 s30, s13, 1
	v_lshl_add_u64 v[20:21], v[20:21], 0, s[30:31]
	v_mov_b32_e32 v109, v1
	v_lshl_add_u64 v[112:113], v[20:21], 0, v[108:109]
	v_lshrrev_b32_e32 v212, 2, v201
	v_and_b32_e32 v213, 3, v201
	v_lshl_add_u32 v210, v213, 4, v212
	v_lshlrev_b32_e32 v210, 2, v210
	v_and_b32_e32 v214, 15, v201
	v_lshrrev_b32_e32 v215, 4, v201
	v_lshl_add_u32 v211, v214, 2, v215
	v_lshlrev_b32_e32 v211, 2, v211
	v_sub_u32_e32 v212, v212, v214
	v_sub_u32_e32 v213, v213, v215
	v_mul_lo_u32 v212, v212, s69
	v_lshl_add_u32 v212, v213, 3, v212
	v_ashrrev_i32_e32 v213, 31, v212
	v_lshl_add_u64 v[112:113], v[112:113], 0, v[212:213]
	global_load_dwordx2 v[128:129], v[112:113], off offset:2048
	global_load_dwordx2 v[126:127], v[112:113], off offset:2080
	global_load_dwordx2 v[124:125], v[112:113], off offset:2112
	global_load_dwordx2 v[122:123], v[112:113], off offset:2144
	global_load_dwordx2 v[120:121], v[112:113], off offset:2176
	global_load_dwordx2 v[118:119], v[112:113], off offset:2208
	global_load_dwordx2 v[116:117], v[112:113], off offset:2240
	global_load_dwordx2 v[114:115], v[112:113], off offset:2272
	v_add_u32_e32 v109, s12, v136
	v_mad_i64_i32 v[130:131], s[12:13], v109, s69, v[18:19]
	v_lshl_add_u64 v[18:19], v[130:131], 0, s[30:31]
	v_and_b32_e32 v161, 0x1ffc, v109
	v_lshl_add_u64 v[132:133], v[18:19], 0, v[0:1]
	v_mov_b32_e32 v18, 0
	v_cmp_eq_u32_e64 s[50:51], 0, v161
	v_cmp_ne_u32_e32 vcc, 0, v161
	v_mov_b32_e32 v22, 0
	v_mov_b32_e32 v23, 0
	v_mov_b32_e32 v24, 0
	v_mov_b32_e32 v25, 0
	s_and_saveexec_b64 s[12:13], vcc
	s_cbranch_execz .LBB0_92
	v_add_co_u32_e32 v20, vcc, 0xffffe000, v132
	s_nop 1
	v_addc_co_u32_e32 v21, vcc, -1, v133, vcc
	global_load_dwordx4 v[22:25], v[20:21], off offset:-2048
